# retention prompt outputs (O rows, final state) and wkv scan outputs (y rows, final state) stored non-temporal: write-once streams that no same-XCD reader follows
# speedup vs baseline: 1.0117x; 1.0020x over previous
; __device__ __forceinline__ void ph_wkv2(const Params& p, int jl, int lane, int wave) {
;     ...
;         const int it = job & 3, h = (job >> 2) & 15, seq = job >> 6, r0 = seq * TP;
;         const unsigned char* rec = p.ws + WS_REC + (size_t)((seq * WH + h) * WC_NCH) * REC_BYTES;
;     ...
;         static_assert(WC_NCH % 2 == 1, "chunk loop unrolled by two plus one");
;         WC_LOAD(RA, rec); WC_LOAD(RB, rec + REC_BYTES);
;         v2u ypk = (v2u){0u, 0u};
;         for (int c = 0; c + 1 < WC_NCH; c += 2) { WC_STEP(RA, RB, c); WC_STEP(RB, RA, c + 1); }
;         WC_STEP(RA, RB, WC_NCH - 1);
;         *(v2u*)(YW + (size_t)(r0 + WC_C * (WC_NCH - 1) + 4 * fq + (fr & 3)) * D + h * WN + 16 * it + (fr & 12)) = ypk;
;     ...
;         float* so = p.out + O_WKVP + ((((size_t)jl * BATCH + seq) * WH + h) * WN + 16 * it + fr) * WN + 4 * fq;
; #pragma unroll
;         for (int jt = 0; jt < 4; ++jt) *(f32x4*)(so + 16 * jt) = Sacc[jt];
.LBB0_130:
	s_waitcnt vmcnt(13)
	v_mov_b32_e32 v204, 0x1000
	s_mov_b64 s[14:15], exec
	s_mov_b64 exec, 1
	ds_write_b32 v1, v204
	s_mov_b64 exec, s[14:15]
	v_add_u32_e32 v54, s12, v182
	v_ashrrev_i32_e32 v55, 31, v54
	v_lshlrev_b64 v[54:55], 11, v[54:55]
	v_lshl_add_u64 v[54:55], s[34:35], 0, v[54:55]
	s_lshl_b32 s94, s13, 1
	v_lshl_add_u64 v[54:55], v[54:55], 0, s[94:95]
	s_lshl_b32 s0, s18, 1
	s_mov_b32 s1, s95
	v_lshl_add_u64 v[54:55], v[54:55], 0, s[0:1]
	v_mov_b32_e32 v171, v1
	v_lshl_add_u64 v[54:55], v[54:55], 0, v[170:171]
	global_store_dwordx2 v[54:55], v[30:31], off nt
	s_waitcnt vmcnt(2)
	v_mfma_f32_16x16x16_bf16 v[54:57], v[102:103], v[32:33], 0
	v_cvt_pk_bf16_f32 v63, v144, v145
	v_cvt_pk_bf16_f32 v62, v142, v143
	v_cvt_pk_bf16_f32 v65, v124, v125
	v_cvt_pk_bf16_f32 v64, v122, v123
	v_mfma_f32_16x16x16_bf16 v[58:61], v[104:105], v[32:33], 0
	s_nop 2
	v_add_f32_e64 v56, v56, 0
	v_add_f32_e64 v57, v57, 0
	v_pk_add_f32 v[54:55], v[54:55], 0 op_sel_hi:[1,0]
	v_cvt_pk_bf16_f32 v67, v120, v121
	v_cvt_pk_bf16_f32 v66, v118, v119
	v_mfma_f32_16x16x32_bf16 v[2:5], v[2:5], v[62:65], v[54:57]
	v_cvt_pk_bf16_f32 v69, v116, v117
	v_cvt_pk_bf16_f32 v68, v114, v115
	v_pk_add_f32 v[60:61], v[60:61], 0 op_sel_hi:[1,0]
	v_pk_add_f32 v[58:59], v[58:59], 0 op_sel_hi:[1,0]
	v_mfma_f32_16x16x32_bf16 v[2:5], v[10:13], v[66:69], v[2:5]
	s_nop 0
	v_mfma_f32_16x16x32_bf16 v[10:13], v[46:49], v[62:65], v[58:61]
	v_mfma_f32_16x16x32_bf16 v[10:13], v[42:45], v[66:69], v[10:13]
	s_nop 4
	v_cvt_pk_bf16_f32 v31, v4, v5
	v_cvt_pk_bf16_f32 v30, v2, v3
	s_nop 1
	v_mfma_f32_16x16x32_bf16 v[6:9], v[6:9], v[30:33], v[114:117]
	v_cndmask_b32_e64 v0, v10, v11, s[4:5]
	s_nop 1
	v_mov_b32_dpp v0, v0 quad_perm:[1,0,3,2] row_mask:0xf bank_mask:0xf bound_ctrl:1
	v_cndmask_b32_e64 v10, v0, v10, s[4:5]
	s_nop 2
	v_pk_mul_f32 v[6:7], v[18:19], v[6:7]
	v_cndmask_b32_e64 v18, v12, v13, s[4:5]
	v_cndmask_b32_e64 v0, v11, v0, s[4:5]
	v_mfma_f32_16x16x32_bf16 v[2:5], v[38:41], v[30:33], v[142:145]
	v_mov_b32_dpp v18, v18 quad_perm:[1,0,3,2] row_mask:0xf bank_mask:0xf bound_ctrl:1
	v_cndmask_b32_e64 v11, v18, v12, s[4:5]
	v_cndmask_b32_e64 v12, v13, v18, s[4:5]
	v_cndmask_b32_e64 v13, v10, v11, s[6:7]
	v_cndmask_b32_e64 v18, v0, v12, s[6:7]
	v_mfma_f32_16x16x32_bf16 v[26:29], v[26:29], v[30:33], v[122:125]
	v_mov_b32_dpp v13, v13 quad_perm:[2,3,0,1] row_mask:0xf bank_mask:0xf bound_ctrl:1
	v_mov_b32_dpp v18, v18 quad_perm:[2,3,0,1] row_mask:0xf bank_mask:0xf bound_ctrl:1
	v_cndmask_b32_e64 v11, v11, v13, s[6:7]
	v_cndmask_b32_e64 v12, v12, v18, s[6:7]
	v_cvt_pk_bf16_f32 v11, v11, v12
	v_add_u32_e32 v12, s12, v183
	v_cndmask_b32_e64 v10, v13, v10, s[6:7]
	v_ashrrev_i32_e32 v13, 31, v12
	v_lshlrev_b64 v[12:13], 11, v[12:13]
	v_lshl_add_u64 v[12:13], s[34:35], 0, v[12:13]
	v_lshl_add_u64 v[12:13], v[12:13], 0, s[94:95]
	v_lshl_add_u64 v[12:13], v[12:13], 0, s[0:1]
	s_ashr_i32 s1, s11, 31
	s_add_u32 s0, s11, s3
	v_cndmask_b32_e64 v0, v18, v0, s[6:7]
	s_addc_u32 s1, s1, 0
	v_cvt_pk_bf16_f32 v10, v10, v0
	v_lshl_add_u64 v[12:13], v[12:13], 0, v[170:171]
	s_lshl_b64 s[0:1], s[0:1], 10
	v_mfma_f32_16x16x32_bf16 v[14:17], v[14:17], v[30:33], v[118:121]
	global_store_dwordx2 v[12:13], v[10:11], off nt
	v_or_b32_e32 v0, s0, v150
	v_mov_b32_e32 v10, s18
	v_or3_b32 v11, s1, 0, 0
	v_or3_b32 v10, v0, s13, v10
	v_lshlrev_b64 v[10:11], 8, v[10:11]
	s_add_i32 s2, s2, s9
	s_sub_i32 s10, s10, s9
	v_pk_mul_f32 v[4:5], v[52:53], v[4:5]
	v_pk_mul_f32 v[2:3], v[50:51], v[2:3]
	v_lshl_add_u64 v[10:11], v[168:169], 0, v[10:11]
	s_cmpk_gt_i32 s2, 0x1ff
	v_pk_mul_f32 v[28:29], v[36:37], v[28:29]
	v_pk_mul_f32 v[26:27], v[34:35], v[26:27]
	v_pk_mul_f32 v[16:17], v[24:25], v[16:17]
	v_pk_mul_f32 v[14:15], v[22:23], v[14:15]
	v_pk_mul_f32 v[8:9], v[20:21], v[8:9]
	global_store_dwordx4 v[10:11], v[2:5], off nt
	global_store_dwordx4 v[10:11], v[26:29], off offset:64 nt
	global_store_dwordx4 v[10:11], v[14:17], off offset:128 nt
	global_store_dwordx4 v[10:11], v[6:9], off offset:192 nt
	s_cbranch_scc1 .LBB0_136
.LBB0_131:
	s_and_b32 s0, s10, 3
	s_ashr_i32 s11, s2, 6
	s_bfe_u32 s18, s2, 0x40002
	v_lshl_or_b32 v0, s0, 9, v180
	s_lshl_b32 s0, s11, 4
	s_or_b32 s0, s0, s18
	s_mul_i32 s1, s0, 0x81
	s_mul_i32 s0, s0, 0x16ad00
	s_and_b32 s22, s2, 3
	v_readlane_b32 s13, v252, 47
	s_mul_hi_i32 s1, s1, 0x2d00
	s_add_u32 s0, s13, s0
	v_readlane_b32 s13, v252, 48
	s_addc_u32 s1, s13, s1
	s_waitcnt vmcnt(0)
; __device__ __forceinline__ void ph_wkv2(const Params& p, int jl, int lane, int wave) {
;     ...
;         WC_LOAD(RA, rec); WC_LOAD(RB, rec + REC_BYTES);
	v_lshl_add_u64 v[134:135], s[0:1], 0, v[152:153]
	s_movk_i32 s8, 0x2000
	v_add_co_u32_e32 v4, vcc, s8, v134
	s_movk_i32 s13, 0x3000
	s_nop 0
	v_addc_co_u32_e32 v5, vcc, 0, v135, vcc
	v_lshl_or_b32 v2, s22, 9, v180
	v_mov_b32_e32 v3, v1
	v_add_co_u32_e32 v6, vcc, s13, v134
	v_lshl_add_u64 v[136:137], s[0:1], 0, v[2:3]
	s_nop 0
	v_addc_co_u32_e32 v7, vcc, 0, v135, vcc
	s_movk_i32 s13, 0x4000
	v_add_co_u32_e32 v2, vcc, s13, v136
	s_movk_i32 s13, 0x5000
	s_nop 0
	v_addc_co_u32_e32 v3, vcc, 0, v137, vcc
	v_add_co_u32_e32 v50, vcc, s13, v134
	s_add_u32 s20, s0, 0x3d00
	s_nop 0
	v_addc_co_u32_e32 v51, vcc, 0, v135, vcc
	global_load_dwordx4 v[98:101], v[4:5], off offset:3328
	global_load_dwordx4 v[94:97], v[6:7], off offset:256
	global_load_dwordx4 v[90:93], v[6:7], off offset:1280
	global_load_dwordx4 v[78:81], v[6:7], off offset:2304
	s_addc_u32 s21, s1, 0
	global_load_dwordx2 v[108:109], v[2:3], off offset:3328
	global_load_dwordx4 v[14:17], v[4:5], off offset:2048
	v_add_co_u32_e32 v2, vcc, s8, v136
	v_lshl_add_u64 v[6:7], s[20:21], 0, v[152:153]
	s_nop 0
	v_addc_co_u32_e32 v3, vcc, 0, v137, vcc
	global_load_dwordx4 v[66:69], v[6:7], off
	global_load_dwordx2 v[4:5], v[2:3], off
	v_lshl_add_u64 v[6:7], s[20:21], 0, v[154:155]
	global_load_dwordx4 v[62:65], v[6:7], off
	v_lshl_add_u64 v[6:7], s[20:21], 0, v[156:157]
	global_load_dwordx4 v[58:61], v[6:7], off
	v_lshl_add_u64 v[6:7], s[20:21], 0, v[158:159]
	s_add_u32 s20, s0, 0x5900
	s_addc_u32 s21, s1, 0
	global_load_dwordx4 v[54:57], v[6:7], off
	v_lshl_add_u64 v[6:7], s[20:21], 0, v[160:161]
	global_load_dwordx4 v[86:89], v[6:7], off
	v_lshl_add_u64 v[6:7], s[20:21], 0, v[162:163]
	s_mul_i32 s19, s18, 0x81
	global_load_dwordx4 v[82:85], v[6:7], off
	v_lshl_add_u64 v[6:7], s[20:21], 0, v[164:165]
	s_lshl_b32 s13, s18, 6
	s_lshl_b32 s18, s18, 7
	global_load_dwordx4 v[74:77], v[6:7], off
	v_lshl_add_u64 v[6:7], s[20:21], 0, v[166:167]
	s_add_u32 s20, s34, s18
	s_addc_u32 s21, s35, 0
	s_lshl_b32 s18, s22, 4
	s_lshl_b32 s22, s22, 5
	s_add_u32 s20, s20, s22
	s_addc_u32 s21, s21, 0
	v_mov_b32_e32 v171, v1
	v_lshl_add_u64 v[172:173], s[20:21], 0, v[170:171]
	s_add_u32 s20, s0, 0x2c00
	s_addc_u32 s21, s1, 0
	v_lshl_add_u64 v[2:3], s[20:21], 0, v[166:167]
	global_load_dwordx4 v[70:73], v[6:7], off
	global_load_dwordx4 v[110:113], v[50:51], off offset:1280
	s_mul_i32 s12, s11, 0x810
	global_load_dwordx4 v[6:9], v[2:3], off
	v_lshl_add_u64 v[2:3], s[20:21], 0, v[164:165]
	global_load_dwordx4 v[10:13], v[2:3], off
	v_lshl_add_u64 v[2:3], s[20:21], 0, v[162:163]
	global_load_dwordx4 v[18:21], v[2:3], off
	v_lshl_add_u64 v[2:3], s[20:21], 0, v[160:161]
	s_add_u32 s20, s0, 0x1000
	s_addc_u32 s21, s1, 0
	global_load_dwordx4 v[26:29], v[2:3], off
	v_lshl_add_u64 v[2:3], s[20:21], 0, v[158:159]
	global_load_dwordx4 v[22:25], v[2:3], off
	v_lshl_add_u64 v[2:3], s[20:21], 0, v[156:157]
	global_load_dwordx4 v[30:33], v[2:3], off
	v_lshl_add_u64 v[2:3], s[20:21], 0, v[154:155]
	global_load_dwordx4 v[34:37], v[2:3], off
	v_lshl_add_u64 v[2:3], s[20:21], 0, v[152:153]
	global_load_dwordx4 v[38:41], v[2:3], off
	global_load_dwordx4 v[42:45], v[134:135], off offset:3072
	global_load_dwordx4 v[46:49], v[134:135], off offset:2048
	global_load_dwordx4 v[102:105], v[134:135], off offset:1024
	global_load_dwordx4 v[114:117], v[134:135], off
	s_waitcnt vmcnt(20)
	v_mfma_f32_16x16x16_bf16 v[122:125], v[14:15], v[4:5], 0
	v_readlane_b32 s20, v253, 59
	v_readlane_b32 s22, v253, 61
	v_readlane_b32 s23, v253, 62
	v_readlane_b32 s21, v253, 60
	s_nop 3
	v_pk_add_f32 v[124:125], v[124:125], 0 op_sel_hi:[1,0]
	v_mov_b64_e32 v[120:121], s[22:23]
	v_mov_b64_e32 v[118:119], s[20:21]
	v_pk_add_f32 v[122:123], v[122:123], 0 op_sel_hi:[1,0]
	v_mfma_f32_16x16x16_bf16 v[14:17], v[16:17], v[4:5], 0
	s_add_u32 s20, s0, 0x6a00
	s_addc_u32 s21, s1, 0
	v_or_b32_e32 v106, s12, v181
	s_waitcnt vmcnt(0)
	v_mfma_f32_16x16x32_bf16 v[114:117], v[114:117], v[118:121], v[122:125]
	s_nop 2
	v_add_f32_e64 v16, v16, 0
	v_add_f32_e64 v17, v17, 0
	v_pk_add_f32 v[14:15], v[14:15], 0 op_sel_hi:[1,0]
	s_mov_b32 s8, 0x8000
	v_mfma_f32_16x16x32_bf16 v[102:105], v[102:105], v[118:121], v[114:117]
	v_add_u32_e32 v174, s12, v184
	v_mfma_f32_16x16x32_bf16 v[14:17], v[46:49], v[118:121], v[14:17]
	v_mfma_f32_16x16x32_bf16 v[130:133], v[42:45], v[118:121], v[14:17]
	s_nop 4
	v_cvt_pk_bf16_f32 v3, v104, v105
	v_cvt_pk_bf16_f32 v2, v102, v103
	s_nop 1
	v_mfma_f32_16x16x32_bf16 v[14:17], v[38:41], v[2:5], 0
	v_cndmask_b32_e64 v107, v130, v131, s[4:5]
	v_cndmask_b32_e64 v138, v132, v133, s[4:5]
	s_nop 0
	v_mov_b32_dpp v107, v107 quad_perm:[1,0,3,2] row_mask:0xf bank_mask:0xf bound_ctrl:1
	v_mov_b32_dpp v138, v138 quad_perm:[1,0,3,2] row_mask:0xf bank_mask:0xf bound_ctrl:1
	s_nop 2
	v_pk_mul_f32 v[128:129], v[28:29], v[16:17]
	v_pk_mul_f32 v[126:127], v[26:27], v[14:15]
	v_mfma_f32_16x16x32_bf16 v[14:17], v[34:37], v[2:5], 0
	v_cndmask_b32_e64 v130, v107, v130, s[4:5]
	v_cndmask_b32_e64 v107, v131, v107, s[4:5]
	v_cndmask_b32_e64 v131, v138, v132, s[4:5]
	v_cndmask_b32_e64 v132, v133, v138, s[4:5]
	v_cndmask_b32_e64 v133, v130, v131, s[6:7]
	s_nop 2
	v_pk_mul_f32 v[124:125], v[20:21], v[16:17]
	v_pk_mul_f32 v[122:123], v[18:19], v[14:15]
	v_mfma_f32_16x16x32_bf16 v[14:17], v[30:33], v[2:5], 0
	v_cndmask_b32_e64 v138, v107, v132, s[6:7]
	v_mov_b32_dpp v133, v133 quad_perm:[2,3,0,1] row_mask:0xf bank_mask:0xf bound_ctrl:1
	v_cndmask_b32_e64 v130, v133, v130, s[6:7]
	v_mfma_f32_16x16x32_bf16 v[2:5], v[22:25], v[2:5], 0
	v_mov_b32_dpp v138, v138 quad_perm:[2,3,0,1] row_mask:0xf bank_mask:0xf bound_ctrl:1
	s_nop 2
	v_pk_mul_f32 v[120:121], v[12:13], v[16:17]
	v_pk_mul_f32 v[118:119], v[10:11], v[14:15]
	v_cndmask_b32_e64 v107, v138, v107, s[6:7]
	v_cvt_pk_bf16_f32 v130, v130, v107
	v_pk_mul_f32 v[114:115], v[6:7], v[2:3]
	v_add_co_u32_e32 v6, vcc, s33, v134
	v_pk_mul_f32 v[116:117], v[8:9], v[4:5]
	s_nop 0
	v_addc_co_u32_e32 v7, vcc, 0, v135, vcc
	global_load_dwordx4 v[2:5], v[50:51], off offset:2560
	global_load_dwordx4 v[10:13], v[50:51], off offset:3584
	global_load_dwordx4 v[46:49], v[6:7], off offset:512
	global_load_dwordx4 v[42:45], v[6:7], off offset:1536
	v_lshl_add_u64 v[6:7], s[20:21], 0, v[152:153]
	global_load_dwordx4 v[38:41], v[6:7], off
	v_lshl_add_u64 v[6:7], s[20:21], 0, v[154:155]
	global_load_dwordx4 v[26:29], v[6:7], off
	v_lshl_add_u64 v[6:7], s[20:21], 0, v[156:157]
	global_load_dwordx4 v[14:17], v[6:7], off
	v_lshl_add_u64 v[6:7], s[20:21], 0, v[158:159]
	s_add_u32 s20, s0, 0x8600
	s_addc_u32 s21, s1, 0
	v_lshl_add_u64 v[18:19], s[20:21], 0, v[160:161]
	global_load_dwordx4 v[6:9], v[6:7], off
	v_ashrrev_i32_e32 v107, 31, v106
	global_load_dwordx4 v[50:53], v[18:19], off
	v_lshl_add_u64 v[18:19], s[20:21], 0, v[162:163]
	global_load_dwordx4 v[34:37], v[18:19], off
	v_lshl_add_u64 v[18:19], s[20:21], 0, v[164:165]
	global_load_dwordx4 v[22:25], v[18:19], off
	v_lshl_add_u64 v[18:19], s[20:21], 0, v[166:167]
	s_movk_i32 s20, 0x7000
	v_add_co_u32_e32 v30, vcc, s20, v136
	v_cndmask_b32_e64 v131, v131, v133, s[6:7]
	s_nop 0
	v_addc_co_u32_e32 v31, vcc, 0, v137, vcc
	global_load_dwordx2 v[32:33], v[30:31], off offset:2560
	v_add_co_u32_e32 v30, vcc, s8, v134
	v_cndmask_b32_e64 v132, v132, v138, s[6:7]
	v_lshlrev_b64 v[106:107], 11, v[106:107]
	v_addc_co_u32_e32 v31, vcc, 0, v135, vcc
	v_cvt_pk_bf16_f32 v131, v131, v132
	v_lshl_add_u64 v[106:107], v[172:173], 0, v[106:107]
	global_load_dwordx4 v[18:21], v[18:19], off
	v_cvt_pk_bf16_f32 v139, v128, v129
	global_load_dwordx4 v[102:105], v[30:31], off offset:512
	v_cvt_pk_bf16_f32 v138, v126, v127
	global_store_dwordx2 v[106:107], v[130:131], off nt
	v_mfma_f32_16x16x16_bf16 v[130:133], v[110:111], v[108:109], 0
	v_cvt_pk_bf16_f32 v141, v124, v125
	v_cvt_pk_bf16_f32 v140, v122, v123
	v_cvt_pk_bf16_f32 v143, v120, v121
	v_cvt_pk_bf16_f32 v142, v118, v119
	v_cvt_pk_bf16_f32 v145, v116, v117
	s_nop 2
	v_pk_add_f32 v[132:133], v[132:133], 0 op_sel_hi:[1,0]
	v_pk_add_f32 v[130:131], v[130:131], 0 op_sel_hi:[1,0]
	v_cvt_pk_bf16_f32 v144, v114, v115
	v_mfma_f32_16x16x16_bf16 v[110:113], v[112:113], v[108:109], 0
	s_mov_b32 s20, 0x9000
	v_mfma_f32_16x16x32_bf16 v[98:101], v[98:101], v[138:141], v[130:133]
	v_mfma_f32_16x16x32_bf16 v[94:97], v[94:97], v[142:145], v[98:101]
	s_nop 4
	v_add_f32_e64 v112, v112, 0
	v_add_f32_e64 v113, v113, 0
	v_pk_add_f32 v[110:111], v[110:111], 0 op_sel_hi:[1,0]
	s_nop 1
	v_mfma_f32_16x16x32_bf16 v[90:93], v[90:93], v[138:141], v[110:113]
	v_cvt_pk_bf16_f32 v107, v96, v97
	v_cvt_pk_bf16_f32 v106, v94, v95
	v_mfma_f32_16x16x32_bf16 v[130:133], v[78:81], v[142:145], v[90:93]
	s_nop 0
	v_mfma_f32_16x16x32_bf16 v[62:65], v[62:65], v[106:109], v[122:125]
	v_mfma_f32_16x16x32_bf16 v[58:61], v[58:61], v[106:109], v[118:121]
	v_mfma_f32_16x16x32_bf16 v[54:57], v[54:57], v[106:109], v[114:117]
	s_nop 5
	v_mul_f32_e64 v124, v84, v64
	v_mul_f32_e64 v125, v85, v65
	v_pk_mul_f32 v[122:123], v[82:83], v[62:63]
	v_pk_mul_f32 v[120:121], v[76:77], v[60:61]
	v_mfma_f32_16x16x32_bf16 v[66:69], v[66:69], v[106:109], v[126:129]
	v_mul_f32_e64 v118, v74, v58
	v_mul_f32_e64 v119, v75, v59
	v_pk_mul_f32 v[116:117], v[72:73], v[56:57]
	v_pk_mul_f32 v[114:115], v[70:71], v[54:55]
	global_load_dwordx4 v[54:57], v[30:31], off offset:1792
	global_load_dwordx4 v[58:61], v[30:31], off offset:2816
	global_load_dwordx4 v[62:65], v[30:31], off offset:3840
	v_add_co_u32_e32 v30, vcc, s20, v134
	s_add_u32 s20, s0, 0x9700
	s_nop 0
	v_addc_co_u32_e32 v31, vcc, 0, v135, vcc
	s_addc_u32 s21, s1, 0
	v_pk_mul_f32 v[144:145], v[88:89], v[68:69]
	v_pk_mul_f32 v[142:143], v[86:87], v[66:67]
	global_load_dwordx4 v[66:69], v[30:31], off offset:768
	v_lshl_add_u64 v[30:31], s[20:21], 0, v[152:153]
	global_load_dwordx4 v[70:73], v[30:31], off
	v_lshl_add_u64 v[30:31], s[20:21], 0, v[154:155]
	global_load_dwordx4 v[74:77], v[30:31], off
	v_lshl_add_u64 v[30:31], s[20:21], 0, v[156:157]
	s_add_u32 s0, s0, 0xb300
	global_load_dwordx4 v[78:81], v[30:31], off
	v_lshl_add_u64 v[30:31], s[20:21], 0, v[158:159]
	s_addc_u32 s1, s1, 0
	global_load_dwordx4 v[82:85], v[30:31], off
	v_lshl_add_u64 v[30:31], s[0:1], 0, v[160:161]
	global_load_dwordx4 v[106:109], v[30:31], off
	v_lshl_add_u64 v[30:31], s[0:1], 0, v[162:163]
	global_load_dwordx4 v[98:101], v[30:31], off
	v_lshl_add_u64 v[30:31], s[0:1], 0, v[164:165]
	global_load_dwordx4 v[90:93], v[30:31], off
	v_lshl_add_u64 v[30:31], s[0:1], 0, v[166:167]
	s_mov_b32 s0, 0xa000
	global_load_dwordx4 v[86:89], v[30:31], off
	v_add_co_u32_e32 v30, vcc, s0, v136
	s_waitcnt vmcnt(0)
	v_mov_b64_e32 v[140:141], v[88:89]
	v_addc_co_u32_e32 v31, vcc, 0, v137, vcc
	global_load_dwordx2 v[96:97], v[30:31], off offset:1792
	v_add_co_u32_e32 v30, vcc, s0, v134
	s_add_i32 s0, s12, s19
	s_nop 0
	v_addc_co_u32_e32 v31, vcc, 0, v135, vcc
	global_load_dwordx4 v[110:113], v[30:31], off offset:3840
	v_cndmask_b32_e64 v30, v130, v131, s[4:5]
	v_cndmask_b32_e64 v31, v132, v133, s[4:5]
	s_mul_hi_i32 s1, s0, 0x2d00
	v_mov_b32_dpp v30, v30 quad_perm:[1,0,3,2] row_mask:0xf bank_mask:0xf bound_ctrl:1
	v_mov_b32_dpp v31, v31 quad_perm:[1,0,3,2] row_mask:0xf bank_mask:0xf bound_ctrl:1
	v_cndmask_b32_e64 v94, v30, v130, s[4:5]
	v_cndmask_b32_e64 v30, v131, v30, s[4:5]
	v_cndmask_b32_e64 v95, v31, v132, s[4:5]
	v_cndmask_b32_e64 v31, v133, v31, s[4:5]
	v_cndmask_b32_e64 v126, v94, v95, s[6:7]
	v_cndmask_b32_e64 v127, v30, v31, s[6:7]
	s_mulk_i32 s0, 0x2d00
	v_mov_b32_dpp v126, v126 quad_perm:[2,3,0,1] row_mask:0xf bank_mask:0xf bound_ctrl:1
	v_mov_b32_dpp v127, v127 quad_perm:[2,3,0,1] row_mask:0xf bank_mask:0xf bound_ctrl:1
	v_cndmask_b32_e64 v94, v126, v94, s[6:7]
	v_cndmask_b32_e64 v30, v127, v30, s[6:7]
	v_cndmask_b32_e64 v95, v95, v126, s[6:7]
	v_cndmask_b32_e64 v31, v31, v127, s[6:7]
	s_add_u32 s0, s66, s0
	v_mov_b64_e32 v[128:129], v[108:109]
	v_mov_b64_e32 v[132:133], v[100:101]
	v_mov_b64_e32 v[136:137], v[92:93]
	v_cvt_pk_bf16_f32 v31, v95, v31
	v_cvt_pk_bf16_f32 v30, v94, v30
	s_addc_u32 s1, s67, s1
	s_mov_b32 s19, 2
	v_mov_b64_e32 v[126:127], v[106:107]
	v_mov_b64_e32 v[130:131], v[98:99]
	v_mov_b64_e32 v[134:135], v[90:91]
	v_mov_b64_e32 v[138:139], v[86:87]
; __device__ __forceinline__ void ph_wkv2(const Params& p, int jl, int lane, int wave) {
;     ...
;         static_assert(WC_NCH % 2 == 1, "chunk loop unrolled by two plus one");
;         WC_LOAD(RA, rec); WC_LOAD(RB, rec + REC_BYTES);
;         v2u ypk = (v2u){0u, 0u};
;         for (int c = 0; c + 1 < WC_NCH; c += 2) { WC_STEP(RA, RB, c); WC_STEP(RB, RA, c + 1); }
.LBB0_132:
	s_waitcnt vmcnt(15)
	v_mov_b32_e32 v204, s19
	s_mov_b64 s[14:15], exec
	s_mov_b64 exec, 1
	ds_write_b32 v1, v204
	s_mov_b64 exec, s[14:15]
	v_mfma_f32_16x16x16_bf16 v[146:149], v[102:103], v[32:33], 0
	v_cvt_pk_bf16_f32 v177, v144, v145
	v_cvt_pk_bf16_f32 v176, v142, v143
	v_cvt_pk_bf16_f32 v179, v124, v125
	v_cvt_pk_bf16_f32 v178, v122, v123
	v_cvt_pk_bf16_f32 v187, v120, v121
	s_nop 2
	v_pk_add_f32 v[148:149], v[148:149], 0 op_sel_hi:[1,0]
	v_pk_add_f32 v[146:147], v[146:147], 0 op_sel_hi:[1,0]
	v_cvt_pk_bf16_f32 v186, v118, v119
	v_cvt_pk_bf16_f32 v189, v116, v117
	v_mfma_f32_16x16x32_bf16 v[2:5], v[2:5], v[176:179], v[146:149]
	v_cvt_pk_bf16_f32 v188, v114, v115
	v_add_u32_e32 v94, -16, v174
	v_ashrrev_i32_e32 v95, 31, v94
	v_mfma_f32_16x16x32_bf16 v[2:5], v[10:13], v[186:189], v[2:5]
	v_lshlrev_b64 v[94:95], 11, v[94:95]
	v_lshl_add_u64 v[94:95], v[172:173], 0, v[94:95]
	global_store_dwordx2 v[94:95], v[30:31], off nt
	v_mfma_f32_16x16x16_bf16 v[102:105], v[104:105], v[32:33], 0
	s_mov_b32 s20, 0x46f9b000
	s_nop 2
	v_cvt_pk_bf16_f32 v31, v4, v5
	v_cvt_pk_bf16_f32 v30, v2, v3
	v_ashrrev_i32_e32 v175, 31, v174
	s_cmpk_gt_u32 s19, 0x7d
	v_mfma_f32_16x16x32_bf16 v[2:5], v[38:41], v[30:33], v[142:145]
	v_add_f32_e64 v104, v104, 0
	v_add_f32_e64 v105, v105, 0
	v_pk_add_f32 v[102:103], v[102:103], 0 op_sel_hi:[1,0]
	s_nop 1
	v_mfma_f32_16x16x32_bf16 v[10:13], v[46:49], v[176:179], v[102:105]
	s_nop 1
	v_mul_f32_e64 v144, v52, v4
	v_mul_f32_e64 v145, v53, v5
	v_pk_mul_f32 v[142:143], v[50:51], v[2:3]
	v_lshl_add_u64 v[176:177], s[0:1], 0, v[160:161]
	v_mfma_f32_16x16x32_bf16 v[2:5], v[26:29], v[30:33], v[122:125]
	v_lshl_add_u64 v[178:179], s[0:1], 0, v[0:1]
	v_cvt_pk_bf16_f32 v191, v144, v145
	v_cvt_pk_bf16_f32 v190, v142, v143
	v_mfma_f32_16x16x32_bf16 v[146:149], v[42:45], v[186:189], v[10:13]
	s_waitcnt vmcnt(1)
	v_mfma_f32_16x16x16_bf16 v[186:189], v[112:113], v[96:97], 0
	s_nop 1
	v_mul_f32_e64 v124, v36, v4
	v_mul_f32_e64 v125, v37, v5
	v_pk_mul_f32 v[122:123], v[34:35], v[2:3]
	v_cvt_pk_bf16_f32 v193, v124, v125
	v_mfma_f32_16x16x32_bf16 v[2:5], v[14:17], v[30:33], v[118:121]
	v_cvt_pk_bf16_f32 v192, v122, v123
	v_pk_add_f32 v[188:189], v[188:189], 0 op_sel_hi:[1,0]
	v_pk_add_f32 v[186:187], v[186:187], 0 op_sel_hi:[1,0]
	s_nop 4
	v_pk_mul_f32 v[120:121], v[24:25], v[4:5]
	v_pk_mul_f32 v[118:119], v[22:23], v[2:3]
	v_mfma_f32_16x16x32_bf16 v[2:5], v[6:9], v[30:33], v[114:117]
	v_lshl_add_u64 v[30:31], s[0:1], 0, v[152:153]
	v_add_co_u32_e32 v6, vcc, s20, v30
	s_mov_b32 s20, 0x46f9c000
	s_nop 0
	v_addc_co_u32_e32 v7, vcc, 0, v31, vcc
	s_nop 2
	v_pk_mul_f32 v[116:117], v[20:21], v[4:5]
	v_pk_mul_f32 v[114:115], v[18:19], v[2:3]
	global_load_dwordx4 v[2:5], v[6:7], off offset:1280
	global_load_dwordx4 v[10:13], v[6:7], off offset:2304
	global_load_dwordx4 v[46:49], v[6:7], off offset:3328
	v_add_co_u32_e32 v6, vcc, s20, v30
	s_mov_b32 s20, 0x46f9e000
	s_nop 0
	v_addc_co_u32_e32 v7, vcc, 0, v31, vcc
	v_add_co_u32_e32 v94, vcc, s29, v30
	global_load_dwordx4 v[42:45], v[6:7], off offset:256
	global_load_dwordx4 v[38:41], v[6:7], off offset:1280
	global_load_dwordx4 v[26:29], v[6:7], off offset:2304
	global_load_dwordx4 v[14:17], v[6:7], off offset:3328
	v_addc_co_u32_e32 v95, vcc, 0, v31, vcc
	v_add_co_u32_e32 v18, vcc, s20, v176
	global_load_dwordx4 v[6:9], v[94:95], off offset:256
	s_nop 0
	v_addc_co_u32_e32 v19, vcc, 0, v177, vcc
	global_load_dwordx4 v[50:53], v[18:19], off offset:256
	global_load_dwordx4 v[34:37], v[18:19], off offset:320
	global_load_dwordx4 v[22:25], v[18:19], off offset:384
	s_nop 0
	global_load_dwordx4 v[18:21], v[18:19], off offset:448
	v_add_co_u32_e32 v32, vcc, s29, v178
	v_cvt_pk_bf16_f32 v197, v120, v121
	s_nop 0
	v_addc_co_u32_e32 v33, vcc, 0, v179, vcc
	global_load_dwordx2 v[32:33], v[32:33], off offset:1280
	s_nop 0
	global_load_dwordx4 v[102:105], v[94:95], off offset:3328
	v_cndmask_b32_e64 v94, v146, v147, s[4:5]
	v_cndmask_b32_e64 v95, v148, v149, s[4:5]
	v_cvt_pk_bf16_f32 v196, v118, v119
	v_mov_b32_dpp v94, v94 quad_perm:[1,0,3,2] row_mask:0xf bank_mask:0xf bound_ctrl:1
	v_mov_b32_dpp v95, v95 quad_perm:[1,0,3,2] row_mask:0xf bank_mask:0xf bound_ctrl:1
	v_cndmask_b32_e64 v146, v94, v146, s[4:5]
	v_cndmask_b32_e64 v94, v147, v94, s[4:5]
	v_cndmask_b32_e64 v147, v95, v148, s[4:5]
	v_cndmask_b32_e64 v95, v149, v95, s[4:5]
	v_cndmask_b32_e64 v148, v146, v147, s[6:7]
	v_cndmask_b32_e64 v149, v94, v95, s[6:7]
	v_cvt_pk_bf16_f32 v199, v116, v117
	v_mov_b32_dpp v148, v148 quad_perm:[2,3,0,1] row_mask:0xf bank_mask:0xf bound_ctrl:1
	v_mov_b32_dpp v149, v149 quad_perm:[2,3,0,1] row_mask:0xf bank_mask:0xf bound_ctrl:1
	v_cndmask_b32_e64 v146, v148, v146, s[6:7]
	v_cndmask_b32_e64 v94, v149, v94, s[6:7]
	v_cndmask_b32_e64 v147, v147, v148, s[6:7]
	v_cndmask_b32_e64 v95, v95, v149, s[6:7]
	v_cvt_pk_bf16_f32 v95, v147, v95
	v_cvt_pk_bf16_f32 v94, v146, v94
	v_lshlrev_b64 v[146:147], 11, v[174:175]
	v_lshl_add_u64 v[146:147], v[172:173], 0, v[146:147]
	global_store_dwordx2 v[146:147], v[94:95], off nt
	v_mfma_f32_16x16x16_bf16 v[146:149], v[110:111], v[96:97], 0
	v_cvt_pk_bf16_f32 v198, v114, v115
	s_nop 6
	v_pk_add_f32 v[148:149], v[148:149], 0 op_sel_hi:[1,0]
	v_pk_add_f32 v[146:147], v[146:147], 0 op_sel_hi:[1,0]
	s_nop 1
	v_mfma_f32_16x16x32_bf16 v[146:149], v[54:57], v[190:193], v[146:149]
	v_mfma_f32_16x16x32_bf16 v[200:203], v[58:61], v[196:199], v[146:149]
	v_mfma_f32_16x16x32_bf16 v[146:149], v[62:65], v[190:193], v[186:189]
	v_mfma_f32_16x16x32_bf16 v[146:149], v[66:69], v[196:199], v[146:149]
	s_nop 5
	v_cvt_pk_bf16_f32 v95, v202, v203
	v_cvt_pk_bf16_f32 v94, v200, v201
	s_nop 1
	v_mfma_f32_16x16x32_bf16 v[142:145], v[70:73], v[94:97], v[142:145]
	v_mfma_f32_16x16x32_bf16 v[122:125], v[74:77], v[94:97], v[122:125]
	v_mfma_f32_16x16x32_bf16 v[118:121], v[78:81], v[94:97], v[118:121]
	v_mfma_f32_16x16x32_bf16 v[114:117], v[82:85], v[94:97], v[114:117]
	v_mov_b64_e32 v[86:87], v[138:139]
	v_mov_b64_e32 v[90:91], v[134:135]
	v_mov_b64_e32 v[98:99], v[130:131]
	v_mov_b64_e32 v[106:107], v[126:127]
	v_mov_b64_e32 v[88:89], v[140:141]
	v_mov_b64_e32 v[92:93], v[136:137]
	v_mov_b64_e32 v[100:101], v[132:133]
	v_mov_b64_e32 v[108:109], v[128:129]
	s_cbranch_scc1 .LBB0_134
	v_add_co_u32_e32 v66, vcc, 0x46f9e000, v30
	s_nop 1
	v_addc_co_u32_e32 v67, vcc, 0, v31, vcc
	v_add_co_u32_e32 v82, vcc, 0x46f9f000, v30
	global_load_dwordx4 v[54:57], v[66:67], off offset:512
	global_load_dwordx4 v[58:61], v[66:67], off offset:1536
	global_load_dwordx4 v[62:65], v[66:67], off offset:2560
	s_nop 0
	global_load_dwordx4 v[66:69], v[66:67], off offset:3584
	v_addc_co_u32_e32 v83, vcc, 0, v31, vcc
	v_add_co_u32_e32 v94, vcc, 0x46fa0000, v176
	global_load_dwordx4 v[70:73], v[82:83], off offset:512
	global_load_dwordx4 v[74:77], v[82:83], off offset:1536
	global_load_dwordx4 v[78:81], v[82:83], off offset:2560
	s_nop 0
	global_load_dwordx4 v[82:85], v[82:83], off offset:3584
	v_addc_co_u32_e32 v95, vcc, 0, v177, vcc
	global_load_dwordx4 v[126:129], v[94:95], off offset:3584
	global_load_dwordx4 v[130:133], v[94:95], off offset:3648
	global_load_dwordx4 v[134:137], v[94:95], off offset:3712
	global_load_dwordx4 v[138:141], v[94:95], off offset:3776
	v_add_co_u32_e32 v94, vcc, 0x46fa0000, v178
	s_nop 1
	v_addc_co_u32_e32 v95, vcc, 0, v179, vcc
	v_add_co_u32_e32 v30, vcc, 0x46fa0000, v30
	s_nop 1
	v_addc_co_u32_e32 v31, vcc, 0, v31, vcc
	global_load_dwordx2 v[96:97], v[94:95], off offset:512
	global_load_dwordx4 v[110:113], v[30:31], off offset:2560

; __device__ __forceinline__ void ph_ret_fast(const Params& p, int jl, LAS unsigned char* lds, int tid, int lane, int wave) {
;     ...
;             for (int dt = 0; dt < 2; ++dt)
; #pragma unroll
;                 for (int et = 0; et < 4; ++et) Sacc[dt][et] = Sacc[dt][et] * (g128 / g127);
;             {
;                 bf16x8 Kt[2][2], Vt[2][4];
;     ...
;                 RT_RD4(0, 0);
; #pragma unroll
;                 for (int s = 0; s < 4; ++s) {
;                     __builtin_amdgcn_sched_barrier(0);
;                     if (s + 1 < 4) RT_RD4((s + 1) & 1, s + 1);
;                     __builtin_amdgcn_s_setprio(1);
; #pragma unroll
;                     for (int dt = 0; dt < 2; ++dt)
; #pragma unroll
;                         for (int et = 0; et < 4; ++et) Sacc[dt][et] = __builtin_amdgcn_mfma_f32_16x16x32_bf16(Kt[s & 1][dt], Vt[s & 1][et], Sacc[dt][et], 0, 0, 0);
;                     __builtin_amdgcn_s_setprio(0);
;                 }
;                 __builtin_amdgcn_sched_barrier(0);
.LBB0_342:
	ds_read_b64_tr_b16 v[36:37], v200 offset:2112
	ds_read_b64_tr_b16 v[34:35], v200
	ds_read_b64_tr_b16 v[38:39], v200 offset:32
	ds_read_b64_tr_b16 v[40:41], v200 offset:2144
	ds_read_b64_tr_b16 v[44:45], v201 offset:576
	ds_read_b64_tr_b16 v[42:43], v201
	ds_read_b64_tr_b16 v[46:47], v201 offset:32
	ds_read_b64_tr_b16 v[48:49], v201 offset:608
	ds_read_b64_tr_b16 v[50:51], v201 offset:64
	ds_read_b64_tr_b16 v[52:53], v201 offset:640
	ds_read_b64_tr_b16 v[54:55], v201 offset:96
	ds_read_b64_tr_b16 v[56:57], v201 offset:672
	v_mov_b32_e32 v123, v122
	v_pk_mul_f32 v[4:5], v[122:123], v[146:147]
	v_pk_mul_f32 v[2:3], v[124:125], v[144:145]
	v_pk_mul_f32 v[8:9], v[122:123], v[142:143]
	v_pk_mul_f32 v[6:7], v[124:125], v[140:141]
	v_pk_mul_f32 v[12:13], v[122:123], v[138:139]
	v_pk_mul_f32 v[10:11], v[124:125], v[136:137]
	v_pk_mul_f32 v[16:17], v[122:123], v[132:133]
	v_pk_mul_f32 v[14:15], v[124:125], v[128:129]
	v_pk_mul_f32 v[20:21], v[122:123], v[158:159]
	v_pk_mul_f32 v[18:19], v[124:125], v[152:153]
	v_pk_mul_f32 v[24:25], v[122:123], v[150:151]
	v_pk_mul_f32 v[22:23], v[124:125], v[148:149]
	v_pk_mul_f32 v[28:29], v[122:123], v[156:157]
	v_pk_mul_f32 v[26:27], v[124:125], v[154:155]
	v_pk_mul_f32 v[32:33], v[122:123], v[162:163]
	v_pk_mul_f32 v[30:31], v[124:125], v[160:161]
	ds_read_b64_tr_b16 v[60:61], v0 offset:2112
	ds_read_b64_tr_b16 v[58:59], v0
	ds_read_b64_tr_b16 v[64:65], v0 offset:2144
	ds_read_b64_tr_b16 v[62:63], v0 offset:32
	ds_read_b64_tr_b16 v[66:67], v202
	ds_read_b64_tr_b16 v[70:71], v202 offset:32
	ds_read_b64_tr_b16 v[78:79], v202 offset:64
	ds_read_b64_tr_b16 v[82:83], v202 offset:96
	ds_read_b64_tr_b16 v[68:69], v202 offset:576
	ds_read_b64_tr_b16 v[72:73], v202 offset:608
	ds_read_b64_tr_b16 v[80:81], v202 offset:640
	ds_read_b64_tr_b16 v[84:85], v202 offset:672
	s_setprio 1
	s_waitcnt lgkmcnt(14)
	v_mfma_f32_16x16x32_bf16 v[2:5], v[34:37], v[42:45], v[2:5]
	v_mfma_f32_16x16x32_bf16 v[6:9], v[34:37], v[46:49], v[6:9]
	v_mfma_f32_16x16x32_bf16 v[10:13], v[34:37], v[50:53], v[10:13]
	s_waitcnt lgkmcnt(12)
	v_mfma_f32_16x16x32_bf16 v[14:17], v[34:37], v[54:57], v[14:17]
	v_mfma_f32_16x16x32_bf16 v[18:21], v[38:41], v[42:45], v[18:21]
	v_mfma_f32_16x16x32_bf16 v[22:25], v[38:41], v[46:49], v[22:25]
	v_mfma_f32_16x16x32_bf16 v[26:29], v[38:41], v[50:53], v[26:29]
	v_mfma_f32_16x16x32_bf16 v[30:33], v[38:41], v[54:57], v[30:33]
	s_setprio 0
	ds_read_b64_tr_b16 v[36:37], v203 offset:2112
	ds_read_b64_tr_b16 v[34:35], v203
	ds_read_b64_tr_b16 v[40:41], v203 offset:2144
	ds_read_b64_tr_b16 v[38:39], v203 offset:32
	ds_read_b64_tr_b16 v[42:43], v202 offset:4608
	ds_read_b64_tr_b16 v[46:47], v202 offset:4640
	ds_read_b64_tr_b16 v[50:51], v202 offset:4672
	ds_read_b64_tr_b16 v[54:55], v202 offset:4704
	ds_read_b64_tr_b16 v[44:45], v202 offset:5184
	ds_read_b64_tr_b16 v[48:49], v202 offset:5216
	ds_read_b64_tr_b16 v[52:53], v202 offset:5248
	ds_read_b64_tr_b16 v[56:57], v202 offset:5280
	s_setprio 1
	s_waitcnt lgkmcnt(14)
	v_mfma_f32_16x16x32_bf16 v[2:5], v[58:61], v[66:69], v[2:5]
	v_mfma_f32_16x16x32_bf16 v[6:9], v[58:61], v[70:73], v[6:9]
	s_waitcnt lgkmcnt(13)
	v_mfma_f32_16x16x32_bf16 v[10:13], v[58:61], v[78:81], v[10:13]
	s_waitcnt lgkmcnt(12)
	v_mfma_f32_16x16x32_bf16 v[14:17], v[58:61], v[82:85], v[14:17]
	v_mfma_f32_16x16x32_bf16 v[18:21], v[62:65], v[66:69], v[18:21]
	v_mfma_f32_16x16x32_bf16 v[22:25], v[62:65], v[70:73], v[22:25]
	v_mfma_f32_16x16x32_bf16 v[26:29], v[62:65], v[78:81], v[26:29]
	v_mfma_f32_16x16x32_bf16 v[30:33], v[62:65], v[82:85], v[30:33]
	s_setprio 0
	ds_read_b64_tr_b16 v[60:61], v204 offset:2112
	ds_read_b64_tr_b16 v[58:59], v204
	ds_read_b64_tr_b16 v[64:65], v204 offset:2144
	ds_read_b64_tr_b16 v[62:63], v204 offset:32
	ds_read_b64_tr_b16 v[66:67], v202 offset:9216
	ds_read_b64_tr_b16 v[70:71], v202 offset:9248
	ds_read_b64_tr_b16 v[78:79], v202 offset:9280
	ds_read_b64_tr_b16 v[82:83], v202 offset:9312
	ds_read_b64_tr_b16 v[68:69], v202 offset:9792
	ds_read_b64_tr_b16 v[72:73], v202 offset:9824
	ds_read_b64_tr_b16 v[80:81], v202 offset:9856
	ds_read_b64_tr_b16 v[84:85], v202 offset:9888
	s_setprio 1
	s_waitcnt lgkmcnt(14)
	v_mfma_f32_16x16x32_bf16 v[2:5], v[34:37], v[42:45], v[2:5]
	v_mfma_f32_16x16x32_bf16 v[6:9], v[34:37], v[46:49], v[6:9]
	s_waitcnt lgkmcnt(13)
	v_mfma_f32_16x16x32_bf16 v[10:13], v[34:37], v[50:53], v[10:13]
	s_waitcnt lgkmcnt(12)
	v_mfma_f32_16x16x32_bf16 v[14:17], v[34:37], v[54:57], v[14:17]
	v_mfma_f32_16x16x32_bf16 v[18:21], v[38:41], v[42:45], v[18:21]
	v_mfma_f32_16x16x32_bf16 v[22:25], v[38:41], v[46:49], v[22:25]
	v_mfma_f32_16x16x32_bf16 v[26:29], v[38:41], v[50:53], v[26:29]
	v_mfma_f32_16x16x32_bf16 v[30:33], v[38:41], v[54:57], v[30:33]
	s_setprio 0
	s_setprio 1
	s_waitcnt lgkmcnt(3)
; #define LAS __attribute__((address_space(3)))
; __device__ __forceinline__ unsigned cvt_pk_bf16(float lo, float hi) { unsigned r; asm("v_cvt_pk_bf16_f32 %0, %1, %2" : "=v"(r) : "v"(lo), "v"(hi)); return r; }
; #define RT_LOAD_Q(cc) do { int ll_ = lane; asm volatile("" : "+v"(ll_)); const int t_ = 128 * (cc) - 112 + i0 + (ll_ & 15); \
;             _Pragma("unroll") for (int s = 0; s < 8; ++s) Qf[s] = t_ >= 0 ? *(const bf16x8*)(Qg + (size_t)(b * TP + t_) * 2048 + 32 * s + 8 * (ll_ >> 4)) : (bf16x8){0, 0, 0, 0, 0, 0, 0, 0}; } while (0)
; __device__ __forceinline__ void ph_ret_fast(const Params& p, int jl, LAS unsigned char* lds, int tid, int lane, int wave) {
;     ...
;     for (int u = blockIdx.x; u < BATCH * RH * 8; u += gridDim.x) {
;     ...
; #pragma unroll
;             for (int dt = 0; dt < 2; ++dt)
; #pragma unroll
;                 for (int et = 0; et < 4; ++et) Sacc[dt][et] = Sacc[dt][et] * g127;
; #pragma unroll
;             for (int dt = 0; dt < 2; ++dt)
; #pragma unroll
;                 for (int et = 0; et < 4; ++et) { v2u w; w.x = cvt_pk_bf16(Sacc[dt][et][0], Sacc[dt][et][1]); w.y = cvt_pk_bf16(Sacc[dt][et][2], Sacc[dt][et][3]);
;                     *(LAS v2u*)(lds + RT_ST_OFF + (16 * et + fr) * RT_SP + (d0 + 16 * dt + 4 * fq) * 2) = w; }
;             if (c + 1 < 17) RT_LOAD_Q(c + 1);
;         }
;     ...
;         float* so = p.out + O_RETP + ((((size_t)jl * BATCH + b) * RH + h) * RDK) * RDV + 64 * es;
; #pragma unroll
;         for (int dt = 0; dt < 2; ++dt)
; #pragma unroll
;             for (int et = 0; et < 4; ++et)
; #pragma unroll
;                 for (int r = 0; r < 4; ++r) so[(size_t)(d0 + 16 * dt + 4 * fq + r) * RDV + 16 * et + fr] = Sacc[dt][et][r];
	v_mfma_f32_16x16x32_bf16 v[2:5], v[58:61], v[66:69], v[2:5]
	s_waitcnt lgkmcnt(2)
	v_mfma_f32_16x16x32_bf16 v[6:9], v[58:61], v[70:73], v[6:9]
	s_waitcnt lgkmcnt(1)
	v_mfma_f32_16x16x32_bf16 v[10:13], v[58:61], v[78:81], v[10:13]
	s_waitcnt lgkmcnt(0)
	v_mfma_f32_16x16x32_bf16 v[14:17], v[58:61], v[82:85], v[14:17]
	v_mfma_f32_16x16x32_bf16 v[18:21], v[62:65], v[66:69], v[18:21]
	v_mfma_f32_16x16x32_bf16 v[22:25], v[62:65], v[70:73], v[22:25]
	v_mfma_f32_16x16x32_bf16 v[26:29], v[62:65], v[78:81], v[26:29]
	v_mfma_f32_16x16x32_bf16 v[30:33], v[62:65], v[82:85], v[30:33]
	s_setprio 0
	v_readlane_b32 s12, v255, 42
	s_ashr_i32 s1, s12, 31
	v_readlane_b32 s0, v255, 31
	v_mov_b32_e32 v119, v118
	s_add_u32 s0, s12, s0
	v_pk_mul_f32 v[4:5], v[118:119], v[4:5]
	v_pk_mul_f32 v[2:3], v[120:121], v[2:3]
	v_cvt_pk_bf16_f32 v35, v4, v5
	s_addc_u32 s1, s1, 0
	v_cvt_pk_bf16_f32 v34, v2, v3
	v_pk_mul_f32 v[8:9], v[118:119], v[8:9]
	v_pk_mul_f32 v[6:7], v[120:121], v[6:7]
	ds_write_b64 v75, v[34:35]
	v_cvt_pk_bf16_f32 v34, v6, v7
	v_cvt_pk_bf16_f32 v35, v8, v9
	s_lshl_b64 s[0:1], s[0:1], 21
	v_readlane_b32 s12, v252, 58
	v_pk_mul_f32 v[12:13], v[118:119], v[12:13]
	v_pk_mul_f32 v[10:11], v[120:121], v[10:11]
	ds_write_b64 v75, v[34:35] offset:8448
	v_cvt_pk_bf16_f32 v34, v10, v11
	v_cvt_pk_bf16_f32 v35, v12, v13
	s_add_u32 s0, s12, s0
	v_readlane_b32 s12, v252, 59
	v_pk_mul_f32 v[16:17], v[118:119], v[16:17]
	v_pk_mul_f32 v[14:15], v[120:121], v[14:15]
	ds_write_b64 v75, v[34:35] offset:16896
	v_cvt_pk_bf16_f32 v34, v14, v15
	v_cvt_pk_bf16_f32 v35, v16, v17
	s_addc_u32 s1, s12, s1
	s_lshl_b32 s12, s27, 19
	v_pk_mul_f32 v[20:21], v[118:119], v[20:21]
	v_pk_mul_f32 v[18:19], v[120:121], v[18:19]
	ds_write_b64 v77, v[34:35]
	v_cvt_pk_bf16_f32 v34, v18, v19
	v_cvt_pk_bf16_f32 v35, v20, v21
	s_add_u32 s0, s0, s12
	v_readlane_b32 s12, v255, 44
	v_pk_mul_f32 v[24:25], v[118:119], v[24:25]
	v_pk_mul_f32 v[22:23], v[120:121], v[22:23]
	ds_write_b64 v74, v[34:35]
	v_cvt_pk_bf16_f32 v34, v22, v23
	v_cvt_pk_bf16_f32 v35, v24, v25
	s_addc_u32 s1, s1, 0
	s_lshl_b32 s12, s12, 2
	v_pk_mul_f32 v[28:29], v[118:119], v[28:29]
	v_pk_mul_f32 v[26:27], v[120:121], v[26:27]
	ds_write_b64 v74, v[34:35] offset:8448
	v_cvt_pk_bf16_f32 v34, v26, v27
	v_cvt_pk_bf16_f32 v35, v28, v29
	s_add_u32 s0, s0, s12
	v_pk_mul_f32 v[32:33], v[118:119], v[32:33]
	v_pk_mul_f32 v[30:31], v[120:121], v[30:31]
	ds_write_b64 v74, v[34:35] offset:16896
	v_cvt_pk_bf16_f32 v34, v30, v31
	v_cvt_pk_bf16_f32 v35, v32, v33
	s_addc_u32 s1, s1, 0
	v_mov_b32_e32 v117, v1
	ds_write_b64 v76, v[34:35]
	v_lshl_add_u64 v[34:35], s[0:1], 0, v[116:117]
	v_lshl_add_u64 v[36:37], v[34:35], 0, v[98:99]
	v_lshl_add_u64 v[38:39], v[34:35], 0, v[100:101]
	global_store_dword v[36:37], v2, off nt
	global_store_dword v[38:39], v3, off nt
	v_lshl_add_u64 v[2:3], v[34:35], 0, v[102:103]
	v_lshl_add_u64 v[40:41], v[34:35], 0, v[104:105]
	global_store_dword v[2:3], v4, off nt
	global_store_dword v[40:41], v5, off nt
	global_store_dword v[36:37], v6, off offset:64 nt
	global_store_dword v[38:39], v7, off offset:64 nt
	global_store_dword v[2:3], v8, off offset:64 nt
	global_store_dword v[40:41], v9, off offset:64 nt
	global_store_dword v[36:37], v10, off offset:128 nt
	global_store_dword v[38:39], v11, off offset:128 nt
	global_store_dword v[2:3], v12, off offset:128 nt
	global_store_dword v[40:41], v13, off offset:128 nt
	global_store_dword v[36:37], v14, off offset:192 nt
	global_store_dword v[38:39], v15, off offset:192 nt
	global_store_dword v[2:3], v16, off offset:192 nt
	global_store_dword v[40:41], v17, off offset:192 nt
	v_lshl_add_u64 v[2:3], v[34:35], 0, v[106:107]
	v_lshl_add_u64 v[4:5], v[34:35], 0, v[108:109]
	v_lshl_add_u64 v[6:7], v[34:35], 0, v[110:111]
	v_lshl_add_u64 v[8:9], v[34:35], 0, v[112:113]
	global_store_dword v[2:3], v18, off nt
	global_store_dword v[4:5], v19, off nt
	global_store_dword v[6:7], v20, off nt
	global_store_dword v[8:9], v21, off nt
	global_store_dword v[2:3], v22, off offset:64 nt
	global_store_dword v[4:5], v23, off offset:64 nt
	global_store_dword v[6:7], v24, off offset:64 nt
	global_store_dword v[8:9], v25, off offset:64 nt
	global_store_dword v[2:3], v26, off offset:128 nt
	global_store_dword v[4:5], v27, off offset:128 nt
	global_store_dword v[6:7], v28, off offset:128 nt
	global_store_dword v[8:9], v29, off offset:128 nt
	global_store_dword v[2:3], v30, off offset:192 nt
	global_store_dword v[4:5], v31, off offset:192 nt
	global_store_dword v[6:7], v32, off offset:192 nt
	global_store_dword v[8:9], v33, off offset:192 nt
	s_load_dword s0, s[88:89], 0x0
	s_waitcnt lgkmcnt(0)
	s_add_i32 s13, s0, s13
	s_cmpk_gt_i32 s13, 0xff
	s_cbranch_scc1 .LBB0_457

; __device__ __forceinline__ v2u pk4(const f32x4 v) { return __builtin_bit_cast(v2u, __builtin_convertvector(v, bf4v)); }
; __device__ __forceinline__ void ph_ret_fast(const Params& p, int jl, LAS unsigned char* lds, int tid, int lane, int wave) {
;     ...
;             {
;                 v2u ow[4];
; #pragma unroll
;                 for (int et = 0; et < 4; ++et) { float oq[4] = {Oacc[et][0], Oacc[et][1], Oacc[et][2], Oacc[et][3]}; quad_transpose4(oq, fr & 3); ow[et] = pk4((f32x4){oq[0], oq[1], oq[2], oq[3]}); }
;                 const int t_ = 128 * c - 112 + i0 + 4 * fq + (fr & 3);
;                 if (t_ >= 0) { bf16* op = O + (size_t)(b * TP + t_) * RV + 512 * h + 64 * es + (fr & 12);
; #pragma unroll
;                     for (int et = 0; et < 4; ++et) *(v2u*)(op + 16 * et) = ow[et]; }
;             }
.LBB0_422:
	s_nop 1
	v_cndmask_b32_e64 v0, v54, v55, s[6:7]
	v_cndmask_b32_e64 v58, v56, v57, s[6:7]
	v_cndmask_b32_e64 v60, v44, v45, s[6:7]
	v_mov_b32_dpp v59, v0 quad_perm:[1,0,3,2] row_mask:0xf bank_mask:0xf bound_ctrl:1
	v_cndmask_b32_e64 v0, v59, v54, s[6:7]
	v_cndmask_b32_e64 v54, v55, v59, s[6:7]
	v_cndmask_b32_e64 v59, v42, v43, s[6:7]
	v_cndmask_b32_e64 v61, v38, v39, s[6:7]
	v_cndmask_b32_e64 v62, v40, v41, s[6:7]
	v_cndmask_b32_e64 v63, v30, v31, s[6:7]
	v_cndmask_b32_e64 v64, v32, v33, s[6:7]
	v_mov_b32_dpp v58, v58 quad_perm:[1,0,3,2] row_mask:0xf bank_mask:0xf bound_ctrl:1
	v_mov_b32_dpp v59, v59 quad_perm:[1,0,3,2] row_mask:0xf bank_mask:0xf bound_ctrl:1
	v_mov_b32_dpp v60, v60 quad_perm:[1,0,3,2] row_mask:0xf bank_mask:0xf bound_ctrl:1
	v_mov_b32_dpp v61, v61 quad_perm:[1,0,3,2] row_mask:0xf bank_mask:0xf bound_ctrl:1
	v_mov_b32_dpp v62, v62 quad_perm:[1,0,3,2] row_mask:0xf bank_mask:0xf bound_ctrl:1
	v_mov_b32_dpp v63, v63 quad_perm:[1,0,3,2] row_mask:0xf bank_mask:0xf bound_ctrl:1
	v_mov_b32_dpp v64, v64 quad_perm:[1,0,3,2] row_mask:0xf bank_mask:0xf bound_ctrl:1
	v_cndmask_b32_e64 v55, v58, v56, s[6:7]
	v_cndmask_b32_e64 v56, v57, v58, s[6:7]
	v_cndmask_b32_e64 v42, v59, v42, s[6:7]
	v_cndmask_b32_e64 v43, v43, v59, s[6:7]
	v_cndmask_b32_e64 v44, v60, v44, s[6:7]
	v_cndmask_b32_e64 v45, v45, v60, s[6:7]
	v_cndmask_b32_e64 v38, v61, v38, s[6:7]
	v_cndmask_b32_e64 v39, v39, v61, s[6:7]
	v_cndmask_b32_e64 v40, v62, v40, s[6:7]
	v_cndmask_b32_e64 v41, v41, v62, s[6:7]
	v_cndmask_b32_e64 v30, v63, v30, s[6:7]
	v_cndmask_b32_e64 v31, v31, v63, s[6:7]
	v_cndmask_b32_e64 v32, v64, v32, s[6:7]
	v_cndmask_b32_e64 v33, v33, v64, s[6:7]
	s_add_i32 s0, s14, s27
	v_cndmask_b32_e64 v57, v0, v55, s[8:9]
	v_cndmask_b32_e64 v58, v54, v56, s[8:9]
	v_cndmask_b32_e64 v59, v42, v44, s[8:9]
	v_cndmask_b32_e64 v60, v43, v45, s[8:9]
	v_cndmask_b32_e64 v61, v38, v40, s[8:9]
	v_cndmask_b32_e64 v62, v39, v41, s[8:9]
	v_cndmask_b32_e64 v63, v30, v32, s[8:9]
	v_cndmask_b32_e64 v64, v31, v33, s[8:9]
	s_add_i32 s1, s0, 0xffffff90
	v_mov_b32_dpp v57, v57 quad_perm:[2,3,0,1] row_mask:0xf bank_mask:0xf bound_ctrl:1
	v_mov_b32_dpp v58, v58 quad_perm:[2,3,0,1] row_mask:0xf bank_mask:0xf bound_ctrl:1
	v_mov_b32_dpp v59, v59 quad_perm:[2,3,0,1] row_mask:0xf bank_mask:0xf bound_ctrl:1
	v_mov_b32_dpp v60, v60 quad_perm:[2,3,0,1] row_mask:0xf bank_mask:0xf bound_ctrl:1
	v_mov_b32_dpp v61, v61 quad_perm:[2,3,0,1] row_mask:0xf bank_mask:0xf bound_ctrl:1
	v_mov_b32_dpp v62, v62 quad_perm:[2,3,0,1] row_mask:0xf bank_mask:0xf bound_ctrl:1
	v_mov_b32_dpp v63, v63 quad_perm:[2,3,0,1] row_mask:0xf bank_mask:0xf bound_ctrl:1
	s_cmp_lt_i32 s1, 0
	v_mov_b32_dpp v64, v64 quad_perm:[2,3,0,1] row_mask:0xf bank_mask:0xf bound_ctrl:1
	s_cbranch_scc1 .LBB0_424
	v_cndmask_b32_e64 v65, v64, v31, s[8:9]
	v_cndmask_b32_e64 v31, v32, v63, s[8:9]
	v_cndmask_b32_e64 v32, v33, v64, s[8:9]
	v_cvt_pk_bf16_f32 v31, v31, v32
	v_cndmask_b32_e64 v32, v61, v38, s[8:9]
	v_cndmask_b32_e64 v38, v62, v39, s[8:9]
	v_cndmask_b32_e64 v33, v40, v61, s[8:9]
	v_cndmask_b32_e64 v39, v41, v62, s[8:9]
	v_cvt_pk_bf16_f32 v33, v33, v39
	v_cndmask_b32_e64 v39, v44, v59, s[8:9]
	v_cndmask_b32_e64 v41, v45, v60, s[8:9]
	v_cvt_pk_bf16_f32 v32, v32, v38
	v_cndmask_b32_e64 v38, v59, v42, s[8:9]
	v_cvt_pk_bf16_f32 v39, v39, v41
	v_cndmask_b32_e64 v41, v55, v57, s[8:9]
	v_cndmask_b32_e64 v42, v56, v58, s[8:9]
	v_cvt_pk_bf16_f32 v41, v41, v42
	v_add_u32_e32 v42, s27, v206
	v_cndmask_b32_e64 v40, v60, v43, s[8:9]
	v_ashrrev_i32_e32 v43, 31, v42
	v_cvt_pk_bf16_f32 v38, v38, v40
	v_cndmask_b32_e64 v0, v57, v0, s[8:9]
	v_cndmask_b32_e64 v40, v58, v54, s[8:9]
	v_lshlrev_b64 v[42:43], 12, v[42:43]
	v_cndmask_b32_e64 v30, v63, v30, s[8:9]
	v_cvt_pk_bf16_f32 v40, v0, v40
	v_lshl_add_u64 v[42:43], v[126:127], 0, v[42:43]
	v_cvt_pk_bf16_f32 v30, v30, v65
	global_store_dwordx2 v[42:43], v[40:41], off nt
	global_store_dwordx2 v[42:43], v[38:39], off offset:32 nt
	global_store_dwordx2 v[42:43], v[32:33], off offset:64 nt
	global_store_dwordx2 v[42:43], v[30:31], off offset:96 nt

; __device__ __forceinline__ v2u pk4(const f32x4 v) { return __builtin_bit_cast(v2u, __builtin_convertvector(v, bf4v)); }
; __device__ __forceinline__ void ph_ret_fast(const Params& p, int jl, LAS unsigned char* lds, int tid, int lane, int wave) {
;     ...
;             {
;                 v2u ow[4];
; #pragma unroll
;                 for (int et = 0; et < 4; ++et) { float oq[4] = {Oacc[et][0], Oacc[et][1], Oacc[et][2], Oacc[et][3]}; quad_transpose4(oq, fr & 3); ow[et] = pk4((f32x4){oq[0], oq[1], oq[2], oq[3]}); }
;                 const int t_ = 128 * c - 112 + i0 + 4 * fq + (fr & 3);
;                 if (t_ >= 0) { bf16* op = O + (size_t)(b * TP + t_) * RV + 512 * h + 64 * es + (fr & 12);
; #pragma unroll
;                     for (int et = 0; et < 4; ++et) *(v2u*)(op + 16 * et) = ow[et]; }
;             }
.LBB0_453:
	s_nop 5
	v_cndmask_b32_e64 v14, v22, v23, s[6:7]
	v_cndmask_b32_e64 v15, v24, v25, s[6:7]
	v_cndmask_b32_e64 v2, v30, v31, s[6:7]
	v_mov_b32_dpp v16, v14 quad_perm:[1,0,3,2] row_mask:0xf bank_mask:0xf bound_ctrl:1
	v_mov_b32_dpp v17, v15 quad_perm:[1,0,3,2] row_mask:0xf bank_mask:0xf bound_ctrl:1
	v_cndmask_b32_e64 v3, v32, v33, s[6:7]
	v_cndmask_b32_e64 v8, v26, v27, s[6:7]
	v_cndmask_b32_e64 v9, v28, v29, s[6:7]
	v_cndmask_b32_e64 v14, v16, v22, s[6:7]
	v_cndmask_b32_e64 v15, v23, v16, s[6:7]
	v_cndmask_b32_e64 v16, v17, v24, s[6:7]
	v_cndmask_b32_e64 v17, v25, v17, s[6:7]
	v_cndmask_b32_e64 v24, v18, v19, s[6:7]
	v_cndmask_b32_e64 v25, v20, v21, s[6:7]
	v_mov_b32_dpp v4, v2 quad_perm:[1,0,3,2] row_mask:0xf bank_mask:0xf bound_ctrl:1
	v_mov_b32_dpp v5, v3 quad_perm:[1,0,3,2] row_mask:0xf bank_mask:0xf bound_ctrl:1
	v_mov_b32_dpp v10, v8 quad_perm:[1,0,3,2] row_mask:0xf bank_mask:0xf bound_ctrl:1
	v_mov_b32_dpp v11, v9 quad_perm:[1,0,3,2] row_mask:0xf bank_mask:0xf bound_ctrl:1
	v_mov_b32_dpp v24, v24 quad_perm:[1,0,3,2] row_mask:0xf bank_mask:0xf bound_ctrl:1
	v_mov_b32_dpp v25, v25 quad_perm:[1,0,3,2] row_mask:0xf bank_mask:0xf bound_ctrl:1
	v_cndmask_b32_e64 v2, v4, v30, s[6:7]
	v_cndmask_b32_e64 v3, v31, v4, s[6:7]
	v_cndmask_b32_e64 v4, v5, v32, s[6:7]
	v_cndmask_b32_e64 v5, v33, v5, s[6:7]
	v_cndmask_b32_e64 v8, v10, v26, s[6:7]
	v_cndmask_b32_e64 v9, v27, v10, s[6:7]
	v_cndmask_b32_e64 v10, v11, v28, s[6:7]
	v_cndmask_b32_e64 v11, v29, v11, s[6:7]
	v_cndmask_b32_e64 v18, v24, v18, s[6:7]
	v_cndmask_b32_e64 v19, v19, v24, s[6:7]
	v_cndmask_b32_e64 v20, v25, v20, s[6:7]
	v_cndmask_b32_e64 v21, v21, v25, s[6:7]
	v_readlane_b32 s0, v255, 21
	v_cndmask_b32_e64 v6, v2, v4, s[8:9]
	v_cndmask_b32_e64 v7, v3, v5, s[8:9]
	v_cndmask_b32_e64 v12, v8, v10, s[8:9]
	v_cndmask_b32_e64 v13, v9, v11, s[8:9]
	v_cndmask_b32_e64 v22, v14, v16, s[8:9]
	v_cndmask_b32_e64 v23, v15, v17, s[8:9]
	v_cndmask_b32_e64 v24, v18, v20, s[8:9]
	v_cndmask_b32_e64 v25, v19, v21, s[8:9]
	v_readlane_b32 s1, v255, 22
	v_mov_b32_dpp v6, v6 quad_perm:[2,3,0,1] row_mask:0xf bank_mask:0xf bound_ctrl:1
	v_mov_b32_dpp v7, v7 quad_perm:[2,3,0,1] row_mask:0xf bank_mask:0xf bound_ctrl:1
	v_mov_b32_dpp v12, v12 quad_perm:[2,3,0,1] row_mask:0xf bank_mask:0xf bound_ctrl:1
	v_mov_b32_dpp v13, v13 quad_perm:[2,3,0,1] row_mask:0xf bank_mask:0xf bound_ctrl:1
	v_mov_b32_dpp v22, v22 quad_perm:[2,3,0,1] row_mask:0xf bank_mask:0xf bound_ctrl:1
	v_mov_b32_dpp v23, v23 quad_perm:[2,3,0,1] row_mask:0xf bank_mask:0xf bound_ctrl:1
	v_mov_b32_dpp v24, v24 quad_perm:[2,3,0,1] row_mask:0xf bank_mask:0xf bound_ctrl:1
	s_andn2_b64 vcc, exec, s[0:1]
	v_mov_b32_dpp v25, v25 quad_perm:[2,3,0,1] row_mask:0xf bank_mask:0xf bound_ctrl:1
	s_cbranch_vccnz .LBB0_342
	v_cndmask_b32_e64 v27, v25, v19, s[8:9]
	v_cndmask_b32_e64 v19, v20, v24, s[8:9]
	v_cndmask_b32_e64 v20, v21, v25, s[8:9]
	v_cvt_pk_bf16_f32 v19, v19, v20
	v_cndmask_b32_e64 v20, v23, v15, s[8:9]
	v_cndmask_b32_e64 v15, v16, v22, s[8:9]
	v_cndmask_b32_e64 v16, v17, v23, s[8:9]
	v_cvt_pk_bf16_f32 v15, v15, v16
	v_cndmask_b32_e64 v16, v13, v9, s[8:9]
	v_cndmask_b32_e64 v9, v10, v12, s[8:9]
	v_cndmask_b32_e64 v10, v11, v13, s[8:9]
	v_or_b32_e32 v26, s94, v182
	v_cvt_pk_bf16_f32 v9, v9, v10
	v_cndmask_b32_e64 v10, v7, v3, s[8:9]
	v_cndmask_b32_e64 v3, v4, v6, s[8:9]
	v_cndmask_b32_e64 v4, v5, v7, s[8:9]
	v_readlane_b32 s0, v255, 38
	v_cvt_pk_bf16_f32 v3, v3, v4
	v_cndmask_b32_e64 v2, v6, v2, s[8:9]
	v_add_u32_e32 v4, s0, v26
	v_ashrrev_i32_e32 v5, 31, v4
	v_lshlrev_b64 v[4:5], 12, v[4:5]
	v_cndmask_b32_e64 v18, v24, v18, s[8:9]
	v_cndmask_b32_e64 v14, v22, v14, s[8:9]
	v_cndmask_b32_e64 v8, v12, v8, s[8:9]
	v_cvt_pk_bf16_f32 v2, v2, v10
	v_lshl_add_u64 v[4:5], v[126:127], 0, v[4:5]
	v_cvt_pk_bf16_f32 v18, v18, v27
	v_cvt_pk_bf16_f32 v14, v14, v20
	v_cvt_pk_bf16_f32 v8, v8, v16
	global_store_dwordx2 v[4:5], v[2:3], off nt
	global_store_dwordx2 v[4:5], v[8:9], off offset:32 nt
	global_store_dwordx2 v[4:5], v[14:15], off offset:64 nt
	global_store_dwordx2 v[4:5], v[18:19], off offset:96 nt
	s_branch .LBB0_342
